# epi7: P7 epilogue prologue de-serialised (both gate/scale load batches + first 5 residual ring loads issued before one counted wait)
# speedup vs baseline: 1.0001x; 1.0001x over previous
.LBB0_571:
	v_mbcnt_lo_u32_b32 v242, -1, 0
	v_mbcnt_hi_u32_b32 v242, -1, v242
	s_lshl_b32 s57, s26, 8
	v_ashrrev_i32_e32 v244, 4, v242
	v_and_or_b32 v130, v242, 15, s92
	s_ashr_i32 s82, s46, 4
	v_lshlrev_b32_e32 v243, 3, v244
	s_or_b32 s0, s57, s93
	v_lshl_add_u32 v176, s46, 8, v130
	v_add_u32_e32 v130, s0, v243
	s_mul_hi_i32 s1, s82, 0x2c00
	s_mul_i32 s0, s82, 0x2c00
	s_lshl_b32 s84, s26, 2
	s_ashr_i32 s85, s84, 31
	s_lshl_b64 s[80:81], s[0:1], 2
	v_readlane_b32 s0, v254, 15
	s_add_u32 s0, s0, s80
	v_readlane_b32 s1, v254, 31
	s_addc_u32 s1, s1, s81
	v_readlane_b32 s34, v255, 2
	v_ashrrev_i32_e32 v131, 31, v130
	s_add_u32 s78, s34, s80
	v_readlane_b32 s34, v255, 3
	v_readlane_b32 s60, v254, 41
	s_addc_u32 s79, s34, s81
	v_lshlrev_b64 v[146:147], 2, v[130:131]
	v_readlane_b32 s70, v254, 51
	v_readlane_b32 s71, v254, 52
	v_lshlrev_b32_e32 v132, 1, v130
	v_lshl_add_u64 v[154:155], s[0:1], 0, v[146:147]
	v_lshl_add_u64 v[156:157], s[70:71], 0, v[146:147]
	v_lshl_add_u64 v[158:159], s[78:79], 0, v[146:147]
	v_lshl_add_u32 v200, v176, 11, v132
	global_load_dwordx4 v[138:141], v[154:155], off offset:16
	global_load_dwordx4 v[142:145], v[154:155], off
	global_load_dwordx4 v[202:205], v[156:157], off offset:16
	global_load_dwordx4 v[206:209], v[156:157], off
	global_load_dwordx4 v[146:149], v[158:159], off offset:16
	global_load_dwordx4 v[150:153], v[158:159], off
	v_add_u32_e32 v181, 0x8000, v200
	v_add_u32_e32 v180, 0x10000, v200
	v_add_u32_e32 v179, 0x18000, v200
	v_add_u32_e32 v178, 0x40000, v200
	v_add_u32_e32 v173, 0x48000, v200
	v_add_u32_e32 v172, 0x50000, v200
	v_add_u32_e32 v253, 0x58000, v200
	v_add_u32_e32 v252, 0x100, v200
	v_add_u32_e32 v251, 0x8100, v200
	v_add_u32_e32 v250, 0x10100, v200
	v_add_u32_e32 v249, 0x18100, v200
	v_add_u32_e32 v248, 0x40100, v200
	v_add_u32_e32 v247, 0x48100, v200
	v_add_u32_e32 v246, 0x50100, v200
	v_add_u32_e32 v245, 0x58100, v200
	v_ashrrev_i32_e32 v177, 31, v176
	v_cmp_gt_u32_e32 vcc, 16, v242
	v_readlane_b32 s61, v254, 42
	v_readlane_b32 s62, v254, 43
	v_readlane_b32 s63, v254, 44
	v_readlane_b32 s64, v254, 45
	v_readlane_b32 s65, v254, 46
	v_readlane_b32 s66, v254, 47
	v_readlane_b32 s67, v254, 48
	v_readlane_b32 s68, v254, 49
	v_readlane_b32 s69, v254, 50
	v_readlane_b32 s72, v254, 53
	v_readlane_b32 s73, v254, 54
	v_readlane_b32 s74, v254, 55
	v_readlane_b32 s75, v254, 56
	global_load_dwordx4 v[130:133], v[154:155], off offset:528
	global_load_dwordx4 v[134:137], v[154:155], off offset:512
	global_load_dwordx4 v[210:213], v[156:157], off offset:528
	global_load_dwordx4 v[214:217], v[156:157], off offset:512
	s_nop 0
	global_load_dwordx4 v[154:157], v[158:159], off offset:528
	s_nop 0
	global_load_dwordx4 v[158:161], v[158:159], off offset:512
	global_load_dwordx4 v[182:185], v200, s[38:39] nt
	global_load_dwordx4 v[186:189], v181, s[38:39] nt
	global_load_dwordx4 v[190:193], v180, s[38:39] nt
	global_load_dwordx4 v[194:197], v179, s[38:39] nt
	global_load_dwordx4 v[162:165], v178, s[38:39] nt
	s_waitcnt vmcnt(5)
	v_pk_add_f32 v[152:153], v[152:153], 1.0 op_sel_hi:[1,0]
	v_pk_add_f32 v[150:151], v[150:151], 1.0 op_sel_hi:[1,0]
	v_pk_mul_f32 v[232:233], v[208:209], v[152:153]
	v_pk_mul_f32 v[234:235], v[206:207], v[150:151]
	v_pk_add_f32 v[206:207], v[148:149], 1.0 op_sel_hi:[1,0]
	v_pk_add_f32 v[208:209], v[146:147], 1.0 op_sel_hi:[1,0]
	v_pk_mul_f32 v[228:229], v[204:205], v[206:207]
	v_pk_mul_f32 v[230:231], v[202:203], v[208:209]
	v_pk_add_f32 v[160:161], v[160:161], 1.0 op_sel_hi:[1,0]
	v_pk_add_f32 v[158:159], v[158:159], 1.0 op_sel_hi:[1,0]
	v_pk_mul_f32 v[224:225], v[216:217], v[160:161]
	v_pk_mul_f32 v[226:227], v[214:215], v[158:159]
	v_pk_add_f32 v[214:215], v[156:157], 1.0 op_sel_hi:[1,0]
	v_pk_add_f32 v[216:217], v[154:155], 1.0 op_sel_hi:[1,0]
	v_pk_mul_f32 v[220:221], v[212:213], v[214:215]
	v_pk_mul_f32 v[222:223], v[210:211], v[216:217]
	global_load_dwordx4 v[158:161], v173, s[38:39] nt
	global_load_dwordx4 v[154:157], v172, s[38:39] nt
	global_load_dwordx4 v[150:153], v253, s[38:39] nt
	global_load_dwordx4 v[146:149], v252, s[38:39] nt
	s_waitcnt vmcnt(8)
	v_lshlrev_b32_e32 v198, 16, v182
	v_and_b32_e32 v199, 0xffff0000, v182
	v_lshlrev_b32_e32 v174, 16, v183
	v_and_b32_e32 v175, 0xffff0000, v183
	v_lshlrev_b32_e32 v182, 16, v184
	v_and_b32_e32 v183, 0xffff0000, v184
	v_lshlrev_b32_e32 v184, 16, v185
	v_and_b32_e32 v185, 0xffff0000, v185
	v_pk_fma_f32 v[174:175], v[128:129], v[144:145], v[174:175]
	v_pk_fma_f32 v[202:203], v[126:127], v[142:143], v[198:199]
	v_pk_fma_f32 v[212:213], v[122:123], v[138:139], v[182:183]
	v_cvt_pk_bf16_f32 v122, v202, v203
	v_cvt_pk_bf16_f32 v123, v174, v175
	v_pk_fma_f32 v[208:209], v[124:125], v[140:141], v[184:185]
	v_cvt_pk_bf16_f32 v124, v212, v213
	v_pk_mul_f32 v[128:129], v[230:231], v[212:213]
	v_cvt_pk_bf16_f32 v125, v208, v209
	global_store_dwordx4 v200, v[122:125], s[38:39]
	v_pk_mul_f32 v[126:127], v[228:229], v[208:209]
	s_waitcnt vmcnt(8)
	v_lshlrev_b32_e32 v182, 16, v188
	v_mul_f32_e32 v122, v203, v203
	v_mul_f32_e32 v123, v175, v175
	v_fmac_f32_e32 v122, v202, v202
	v_fmac_f32_e32 v123, v174, v174
	v_add_f32_e32 v122, v122, v123
	v_mul_f32_e32 v123, v213, v213
	v_fmac_f32_e32 v123, v212, v212
	v_add_f32_e32 v122, v123, v122
	v_mul_f32_e32 v123, v209, v209
	v_fmac_f32_e32 v123, v208, v208
	v_add_f32_e32 v218, v123, v122
	v_pk_mul_f32 v[122:123], v[232:233], v[174:175]
	v_pk_mul_f32 v[124:125], v[234:235], v[202:203]
	v_max_f32_e64 v122, |v122|, |v123|
	v_max_f32_e64 v123, |v126|, |v127|
	v_max_f32_e64 v124, |v124|, |v125|
	v_max3_f32 v123, |v128|, |v129|, v123
	v_max3_f32 v219, v124, v122, v123
	global_load_dwordx4 v[122:125], v251, s[38:39] nt
	v_lshlrev_b32_e32 v126, 16, v186
	v_and_b32_e32 v127, 0xffff0000, v186
	v_lshlrev_b32_e32 v128, 16, v187
	v_and_b32_e32 v129, 0xffff0000, v187
	v_and_b32_e32 v183, 0xffff0000, v188
	v_lshlrev_b32_e32 v184, 16, v189
	v_and_b32_e32 v185, 0xffff0000, v189
	v_pk_fma_f32 v[214:215], v[120:121], v[144:145], v[128:129]
	v_pk_fma_f32 v[216:217], v[118:119], v[142:143], v[126:127]
	v_pk_fma_f32 v[206:207], v[116:117], v[140:141], v[184:185]
	v_pk_fma_f32 v[210:211], v[114:115], v[138:139], v[182:183]
	v_cvt_pk_bf16_f32 v114, v216, v217
	v_cvt_pk_bf16_f32 v115, v214, v215
	s_waitcnt vmcnt(8)
	v_lshlrev_b32_e32 v118, 16, v190
	v_cvt_pk_bf16_f32 v116, v210, v211
	v_cvt_pk_bf16_f32 v117, v206, v207
	global_store_dwordx4 v181, v[114:117], s[38:39]
	global_load_dwordx4 v[114:117], v250, s[38:39] nt
	v_and_b32_e32 v119, 0xffff0000, v190
	v_lshlrev_b32_e32 v120, 16, v191
	v_and_b32_e32 v121, 0xffff0000, v191
	v_lshlrev_b32_e32 v126, 16, v192
	v_and_b32_e32 v127, 0xffff0000, v192
	v_lshlrev_b32_e32 v128, 16, v193
	v_and_b32_e32 v129, 0xffff0000, v193
	v_pk_fma_f32 v[200:201], v[112:113], v[144:145], v[120:121]
	v_pk_fma_f32 v[204:205], v[110:111], v[142:143], v[118:119]
	v_pk_fma_f32 v[192:193], v[108:109], v[140:141], v[128:129]
	v_pk_fma_f32 v[198:199], v[106:107], v[138:139], v[126:127]
	v_cvt_pk_bf16_f32 v106, v204, v205
	v_cvt_pk_bf16_f32 v107, v200, v201
	s_waitcnt vmcnt(9)
	v_lshlrev_b32_e32 v110, 16, v194
	v_cvt_pk_bf16_f32 v108, v198, v199
	v_cvt_pk_bf16_f32 v109, v192, v193
	global_store_dwordx4 v180, v[106:109], s[38:39]
	global_load_dwordx4 v[106:109], v249, s[38:39] nt
	v_and_b32_e32 v111, 0xffff0000, v194
	v_lshlrev_b32_e32 v112, 16, v195
	v_and_b32_e32 v113, 0xffff0000, v195
	v_lshlrev_b32_e32 v118, 16, v196
	v_and_b32_e32 v119, 0xffff0000, v196
	v_lshlrev_b32_e32 v120, 16, v197
	v_and_b32_e32 v121, 0xffff0000, v197
	v_pk_fma_f32 v[190:191], v[104:105], v[144:145], v[112:113]
	v_pk_fma_f32 v[194:195], v[102:103], v[142:143], v[110:111]
	v_pk_fma_f32 v[186:187], v[100:101], v[140:141], v[120:121]
	v_pk_fma_f32 v[188:189], v[98:99], v[138:139], v[118:119]
	v_cvt_pk_bf16_f32 v98, v194, v195
	v_cvt_pk_bf16_f32 v99, v190, v191
	s_waitcnt vmcnt(10)
	v_lshlrev_b32_e32 v102, 16, v162
	v_cvt_pk_bf16_f32 v100, v188, v189
	v_cvt_pk_bf16_f32 v101, v186, v187
	global_store_dwordx4 v179, v[98:101], s[38:39]
	global_load_dwordx4 v[98:101], v248, s[38:39] nt
	v_and_b32_e32 v103, 0xffff0000, v162
	v_lshlrev_b32_e32 v104, 16, v163
	v_and_b32_e32 v105, 0xffff0000, v163
	v_lshlrev_b32_e32 v110, 16, v164
	v_and_b32_e32 v111, 0xffff0000, v164
	v_lshlrev_b32_e32 v112, 16, v165
	v_and_b32_e32 v113, 0xffff0000, v165
	v_pk_fma_f32 v[182:183], v[96:97], v[144:145], v[104:105]
	v_pk_fma_f32 v[184:185], v[94:95], v[142:143], v[102:103]
	v_pk_fma_f32 v[164:165], v[92:93], v[140:141], v[112:113]
	v_pk_fma_f32 v[180:181], v[90:91], v[138:139], v[110:111]
	v_cvt_pk_bf16_f32 v90, v184, v185
	v_cvt_pk_bf16_f32 v91, v182, v183
	s_waitcnt vmcnt(11)
	v_lshlrev_b32_e32 v94, 16, v158
	v_cvt_pk_bf16_f32 v92, v180, v181
	v_cvt_pk_bf16_f32 v93, v164, v165
	global_store_dwordx4 v178, v[90:93], s[38:39]
	global_load_dwordx4 v[90:93], v247, s[38:39] nt
	v_and_b32_e32 v95, 0xffff0000, v158
	v_lshlrev_b32_e32 v96, 16, v159
	v_and_b32_e32 v97, 0xffff0000, v159
	v_lshlrev_b32_e32 v102, 16, v160
	v_and_b32_e32 v103, 0xffff0000, v160
	v_lshlrev_b32_e32 v104, 16, v161
	v_and_b32_e32 v105, 0xffff0000, v161
	v_pk_fma_f32 v[162:163], v[88:89], v[144:145], v[96:97]
	v_pk_fma_f32 v[178:179], v[86:87], v[142:143], v[94:95]
	v_pk_fma_f32 v[158:159], v[84:85], v[140:141], v[104:105]
	v_pk_fma_f32 v[160:161], v[82:83], v[138:139], v[102:103]
	v_cvt_pk_bf16_f32 v82, v178, v179
	v_cvt_pk_bf16_f32 v83, v162, v163
	s_waitcnt vmcnt(12)
	v_lshlrev_b32_e32 v86, 16, v154
	v_cvt_pk_bf16_f32 v84, v160, v161
	v_cvt_pk_bf16_f32 v85, v158, v159
	global_store_dwordx4 v173, v[82:85], s[38:39]
	global_load_dwordx4 v[82:85], v246, s[38:39] nt
	v_and_b32_e32 v87, 0xffff0000, v154
	v_lshlrev_b32_e32 v88, 16, v155
	v_and_b32_e32 v89, 0xffff0000, v155
	v_lshlrev_b32_e32 v94, 16, v156
	v_and_b32_e32 v95, 0xffff0000, v156
	v_lshlrev_b32_e32 v96, 16, v157
	v_and_b32_e32 v97, 0xffff0000, v157
	v_pk_fma_f32 v[154:155], v[80:81], v[144:145], v[88:89]
	v_pk_fma_f32 v[156:157], v[78:79], v[142:143], v[86:87]
	v_pk_fma_f32 v[120:121], v[76:77], v[140:141], v[96:97]
	v_pk_fma_f32 v[128:129], v[74:75], v[138:139], v[94:95]
	v_cvt_pk_bf16_f32 v74, v156, v157
	v_cvt_pk_bf16_f32 v75, v154, v155
	s_waitcnt vmcnt(13)
	v_lshlrev_b32_e32 v78, 16, v150
	v_cvt_pk_bf16_f32 v76, v128, v129
	v_cvt_pk_bf16_f32 v77, v120, v121
	global_store_dwordx4 v172, v[74:77], s[38:39]
	global_load_dwordx4 v[74:77], v245, s[38:39] nt
	v_and_b32_e32 v79, 0xffff0000, v150
	v_lshlrev_b32_e32 v80, 16, v151
	v_and_b32_e32 v81, 0xffff0000, v151
	v_lshlrev_b32_e32 v86, 16, v152
	v_and_b32_e32 v87, 0xffff0000, v152
	v_lshlrev_b32_e32 v88, 16, v153
	v_and_b32_e32 v89, 0xffff0000, v153
	v_pk_fma_f32 v[118:119], v[68:69], v[144:145], v[80:81]
	v_pk_fma_f32 v[126:127], v[66:67], v[142:143], v[78:79]
	v_pk_fma_f32 v[110:111], v[60:61], v[140:141], v[88:89]
	v_pk_fma_f32 v[112:113], v[58:59], v[138:139], v[86:87]
	v_cvt_pk_bf16_f32 v58, v126, v127
	v_cvt_pk_bf16_f32 v59, v118, v119
	s_waitcnt vmcnt(14)
	v_lshlrev_b32_e32 v66, 16, v148
	v_cvt_pk_bf16_f32 v60, v112, v113
	v_cvt_pk_bf16_f32 v61, v110, v111
	global_store_dwordx4 v253, v[58:61], s[38:39]
	v_and_b32_e32 v67, 0xffff0000, v148
	v_lshlrev_b32_e32 v68, 16, v149
	v_lshlrev_b32_e32 v58, 16, v146
	v_and_b32_e32 v59, 0xffff0000, v146
	v_lshlrev_b32_e32 v60, 16, v147
	v_and_b32_e32 v61, 0xffff0000, v147
	v_and_b32_e32 v69, 0xffff0000, v149
	v_pk_fma_f32 v[94:95], v[72:73], v[136:137], v[60:61]
	v_pk_fma_f32 v[104:105], v[70:71], v[134:135], v[58:59]
	v_pk_fma_f32 v[72:73], v[64:65], v[132:133], v[68:69]
	v_cvt_pk_bf16_f32 v58, v104, v105
	v_cvt_pk_bf16_f32 v59, v94, v95
	v_pk_fma_f32 v[88:89], v[62:63], v[130:131], v[66:67]
	v_pk_mul_f32 v[62:63], v[220:221], v[72:73]
	v_cvt_pk_bf16_f32 v60, v88, v89
	v_cvt_pk_bf16_f32 v61, v72, v73
	global_store_dwordx4 v252, v[58:61], s[38:39]
	v_pk_mul_f32 v[64:65], v[222:223], v[88:89]
	s_nop 0
	v_mul_f32_e32 v58, v105, v105
	v_mul_f32_e32 v59, v95, v95
	v_fmac_f32_e32 v58, v104, v104
	v_fmac_f32_e32 v59, v94, v94
	v_add_f32_e32 v58, v58, v59
	v_mul_f32_e32 v59, v89, v89
	v_fmac_f32_e32 v59, v88, v88
	v_add_f32_e32 v58, v59, v58
	v_mul_f32_e32 v59, v73, v73
	v_fmac_f32_e32 v59, v72, v72
	v_add_f32_e32 v58, v59, v58
	v_add_f32_e32 v138, v218, v58
	v_pk_mul_f32 v[58:59], v[224:225], v[94:95]
	v_pk_mul_f32 v[60:61], v[226:227], v[104:105]
	v_max_f32_e64 v58, |v58|, |v59|
	v_max_f32_e64 v59, |v62|, |v63|
	v_max_f32_e64 v60, |v60|, |v61|
	v_max3_f32 v59, |v64|, |v65|, v59
	v_max3_f32 v58, v60, v58, v59
	v_max3_f32 v139, v219, 0, v58
	s_waitcnt vmcnt(14)
	v_lshlrev_b32_e32 v58, 16, v122
	v_and_b32_e32 v59, 0xffff0000, v122
	v_lshlrev_b32_e32 v60, 16, v123
	v_and_b32_e32 v61, 0xffff0000, v123
	v_lshlrev_b32_e32 v62, 16, v124
	v_and_b32_e32 v63, 0xffff0000, v124
	v_lshlrev_b32_e32 v64, 16, v125
	v_and_b32_e32 v65, 0xffff0000, v125
	v_pk_fma_f32 v[96:97], v[56:57], v[136:137], v[60:61]
	v_pk_fma_f32 v[102:103], v[54:55], v[134:135], v[58:59]
	v_pk_fma_f32 v[80:81], v[52:53], v[132:133], v[64:65]
	v_pk_fma_f32 v[86:87], v[50:51], v[130:131], v[62:63]
	v_cvt_pk_bf16_f32 v50, v102, v103
	v_cvt_pk_bf16_f32 v51, v96, v97
	s_waitcnt vmcnt(12)
	v_lshlrev_b32_e32 v54, 16, v116
	v_cvt_pk_bf16_f32 v52, v86, v87
	v_cvt_pk_bf16_f32 v53, v80, v81
	global_store_dwordx4 v251, v[50:53], s[38:39]
	v_and_b32_e32 v55, 0xffff0000, v116
	v_lshlrev_b32_e32 v56, 16, v117
	v_lshlrev_b32_e32 v50, 16, v114
	v_and_b32_e32 v51, 0xffff0000, v114
	v_lshlrev_b32_e32 v52, 16, v115
	v_and_b32_e32 v53, 0xffff0000, v115
	v_and_b32_e32 v57, 0xffff0000, v117
	v_pk_fma_f32 v[70:71], v[48:49], v[136:137], v[52:53]
	v_pk_fma_f32 v[78:79], v[46:47], v[134:135], v[50:51]
	v_pk_fma_f32 v[64:65], v[44:45], v[132:133], v[56:57]
	v_pk_fma_f32 v[68:69], v[42:43], v[130:131], v[54:55]
	v_cvt_pk_bf16_f32 v42, v78, v79
	v_cvt_pk_bf16_f32 v43, v70, v71
	s_waitcnt vmcnt(11)
	v_lshlrev_b32_e32 v46, 16, v108
	v_cvt_pk_bf16_f32 v44, v68, v69
	v_cvt_pk_bf16_f32 v45, v64, v65
	global_store_dwordx4 v250, v[42:45], s[38:39]
	v_and_b32_e32 v47, 0xffff0000, v108
	v_lshlrev_b32_e32 v48, 16, v109
	v_lshlrev_b32_e32 v42, 16, v106
	v_and_b32_e32 v43, 0xffff0000, v106
	v_lshlrev_b32_e32 v44, 16, v107
	v_and_b32_e32 v45, 0xffff0000, v107
	v_and_b32_e32 v49, 0xffff0000, v109
	v_pk_fma_f32 v[62:63], v[40:41], v[136:137], v[44:45]
	v_pk_fma_f32 v[66:67], v[38:39], v[134:135], v[42:43]
	v_pk_fma_f32 v[58:59], v[36:37], v[132:133], v[48:49]
	v_pk_fma_f32 v[60:61], v[34:35], v[130:131], v[46:47]
	v_cvt_pk_bf16_f32 v34, v66, v67
	v_cvt_pk_bf16_f32 v35, v62, v63
	s_waitcnt vmcnt(10)
	v_lshlrev_b32_e32 v38, 16, v100
	v_cvt_pk_bf16_f32 v36, v60, v61
	v_cvt_pk_bf16_f32 v37, v58, v59
	global_store_dwordx4 v249, v[34:37], s[38:39]
	v_and_b32_e32 v39, 0xffff0000, v100
	v_lshlrev_b32_e32 v40, 16, v101
	v_lshlrev_b32_e32 v34, 16, v98
	v_and_b32_e32 v35, 0xffff0000, v98
	v_lshlrev_b32_e32 v36, 16, v99
	v_and_b32_e32 v37, 0xffff0000, v99
	v_and_b32_e32 v41, 0xffff0000, v101
	v_pk_fma_f32 v[54:55], v[32:33], v[136:137], v[36:37]
	v_pk_fma_f32 v[56:57], v[30:31], v[134:135], v[34:35]
	v_pk_fma_f32 v[48:49], v[28:29], v[132:133], v[40:41]
	v_pk_fma_f32 v[52:53], v[26:27], v[130:131], v[38:39]
	v_cvt_pk_bf16_f32 v26, v56, v57
	v_cvt_pk_bf16_f32 v27, v54, v55
	s_waitcnt vmcnt(9)
	v_lshlrev_b32_e32 v30, 16, v92
	v_cvt_pk_bf16_f32 v28, v52, v53
	v_cvt_pk_bf16_f32 v29, v48, v49
	global_store_dwordx4 v248, v[26:29], s[38:39]
	v_and_b32_e32 v31, 0xffff0000, v92
	v_lshlrev_b32_e32 v32, 16, v93
	v_lshlrev_b32_e32 v26, 16, v90
	v_and_b32_e32 v27, 0xffff0000, v90
	v_lshlrev_b32_e32 v28, 16, v91
	v_and_b32_e32 v29, 0xffff0000, v91
	v_and_b32_e32 v33, 0xffff0000, v93
	v_pk_fma_f32 v[46:47], v[24:25], v[136:137], v[28:29]
	v_pk_fma_f32 v[50:51], v[22:23], v[134:135], v[26:27]
	v_pk_fma_f32 v[42:43], v[20:21], v[132:133], v[32:33]
	v_pk_fma_f32 v[44:45], v[18:19], v[130:131], v[30:31]
	v_cvt_pk_bf16_f32 v18, v50, v51
	v_cvt_pk_bf16_f32 v19, v46, v47
	s_waitcnt vmcnt(8)
	v_lshlrev_b32_e32 v22, 16, v84
	v_cvt_pk_bf16_f32 v20, v44, v45
	v_cvt_pk_bf16_f32 v21, v42, v43
	global_store_dwordx4 v247, v[18:21], s[38:39]
	v_and_b32_e32 v23, 0xffff0000, v84
	v_lshlrev_b32_e32 v24, 16, v85
	v_lshlrev_b32_e32 v18, 16, v82
	v_and_b32_e32 v19, 0xffff0000, v82
	v_lshlrev_b32_e32 v20, 16, v83
	v_and_b32_e32 v21, 0xffff0000, v83
	v_and_b32_e32 v25, 0xffff0000, v85
	v_pk_fma_f32 v[38:39], v[16:17], v[136:137], v[20:21]
	v_pk_fma_f32 v[40:41], v[14:15], v[134:135], v[18:19]
	v_pk_fma_f32 v[32:33], v[12:13], v[132:133], v[24:25]
	v_pk_fma_f32 v[36:37], v[10:11], v[130:131], v[22:23]
	v_cvt_pk_bf16_f32 v10, v40, v41
	v_cvt_pk_bf16_f32 v11, v38, v39
	s_waitcnt vmcnt(7)
	v_lshlrev_b32_e32 v14, 16, v76
	v_cvt_pk_bf16_f32 v12, v36, v37
	v_cvt_pk_bf16_f32 v13, v32, v33
	global_store_dwordx4 v246, v[10:13], s[38:39]
	v_and_b32_e32 v15, 0xffff0000, v76
	v_lshlrev_b32_e32 v16, 16, v77
	v_lshlrev_b32_e32 v10, 16, v74
	v_and_b32_e32 v11, 0xffff0000, v74
	v_lshlrev_b32_e32 v12, 16, v75
	v_and_b32_e32 v13, 0xffff0000, v75
	v_and_b32_e32 v17, 0xffff0000, v77
	v_pk_fma_f32 v[30:31], v[8:9], v[136:137], v[12:13]
	v_pk_fma_f32 v[34:35], v[6:7], v[134:135], v[10:11]
	v_pk_fma_f32 v[28:29], v[2:3], v[130:131], v[14:15]
	v_cvt_pk_bf16_f32 v2, v34, v35
	v_cvt_pk_bf16_f32 v3, v30, v31
	v_pk_fma_f32 v[26:27], v[4:5], v[132:133], v[16:17]
	v_cvt_pk_bf16_f32 v4, v28, v29
	v_lshlrev_b64 v[18:19], 7, v[176:177]
	v_cvt_pk_bf16_f32 v5, v26, v27
	global_store_dwordx4 v245, v[2:5], s[38:39]
	s_nop 1
	v_and_b32_e32 v3, 64, v239
	v_xor_b32_e32 v2, 16, v239
	v_add_u32_e32 v3, 64, v3
	v_cmp_lt_i32_e64 s[0:1], v2, v3
	s_nop 1
	v_cndmask_b32_e64 v2, v239, v2, s[0:1]
	v_lshlrev_b32_e32 v122, 2, v2
	v_xor_b32_e32 v2, 32, v239
	v_cmp_lt_i32_e64 s[0:1], v2, v3
	ds_bpermute_b32 v4, v122, v139
	s_waitcnt lgkmcnt(0)
	v_max_f32_e32 v4, v4, v4
	v_cndmask_b32_e64 v2, v239, v2, s[0:1]
	v_lshlrev_b32_e32 v123, 2, v2
	ds_bpermute_b32 v2, v122, v138
	v_max_f32_e32 v4, v139, v4
	ds_bpermute_b32 v5, v123, v4
	s_waitcnt lgkmcnt(1)
	v_add_f32_e32 v2, v138, v2
	ds_bpermute_b32 v3, v123, v2
	s_and_saveexec_b64 s[0:1], vcc
	s_cbranch_execz .LBB0_573
	s_waitcnt lgkmcnt(1)
	v_max_f32_e32 v5, v5, v5
	v_max_f32_e32 v4, v4, v4
	v_max_f32_e32 v5, v4, v5
	s_waitcnt lgkmcnt(0)
	v_add_f32_e32 v4, v2, v3
	v_lshl_add_u64 v[2:3], s[42:43], 0, v[18:19]
	v_lshl_add_u64 v[2:3], s[84:85], 3, v[2:3]
	s_lshl_b32 s40, s91, 3
	v_lshl_add_u64 v[2:3], v[2:3], 0, s[40:41]
	s_cmp_eq_u32 s99, 1
	s_cbranch_scc1 .Lxp_plain_1
	global_store_dwordx2 v[2:3], v[4:5], off sc1
	s_branch .Lxp_done_1
